# dense attention item loop shifted +8 bytes (loop-head offset 4 mod 64), complementary pad after the phase
# baseline (speedup 1.0000x reference)
; DI int fresh_lane() { int l; asm volatile("v_mbcnt_lo_u32_b32 %0, -1, 0\n\tv_mbcnt_hi_u32_b32 %0, -1, %0" : "=v"(l)); return l; }
; #define FRESH_IDS() int tid_ = wave_s * 64 + fresh_lane(); asm volatile("" : "+v"(tid_)); const int tid = tid_, lane = tid & 63, wave = wave_s; (void)tid; (void)lane; (void)wave
; __global__ void __launch_bounds__(512, 2) fwd_kernel(Params p) {
;     ...
;     for (int rep_ = 0; rep_ < REP_ATTNC; ++rep_) { FRESH_IDS();
;         const int G_ = (int)gridDim.x, vcu = (G_ % 8 == 0) ? ((int)blockIdx.x & 7) * (G_ >> 3) + ((int)blockIdx.x >> 3) : (int)blockIdx.x;
;         for (int item = vcu; item < 1024; item += G_) {
;             const int qb = item & 15, head = (item >> 4) & 7, b = item >> 7, kvh = head >> 2;
;             int tl = wave * 64 + fresh_lane(); asm volatile("" : "+v"(tl));
;             const size_t qrow = (size_t)NCTX + (size_t)b * SEQ + qb * 256;
;             __syncthreads();
.LBB0_1525:
	s_or_b64 exec, exec, s[0:1]
	s_and_b32 s1, s75, 7
	s_ashr_i32 s2, s30, 3
	s_mul_i32 s1, s2, s1
	s_ashr_i32 s2, s75, 3
	s_and_b32 s0, s30, 7
	s_add_i32 s1, s1, s2
	s_cmp_eq_u32 s0, 0
	s_waitcnt lgkmcnt(0)
	s_barrier
	v_mbcnt_lo_u32_b32 v0, -1, 0
	v_mbcnt_hi_u32_b32 v0, -1, v0
	s_cselect_b32 s2, s1, s75
	s_mov_b32 s56, 0
	v_add_u32_e32 v0, s74, v0
	s_cmpk_gt_i32 s2, 0x3ff
	s_cbranch_scc1 .LBB0_1547
	s_add_u32 s3, s28, 0x1e500000
	s_addc_u32 s11, s29, 0
	s_add_u32 s0, s28, 0x1e512000
	s_addc_u32 s1, s29, 0
	v_mov_b32_e32 v177, 0
	s_mov_b32 s14, 0x42b504f3
	s_mov_b32 s10, 0x3e0293ee
	v_mov_b32_e32 v180, 0xf149f2ca
	s_mov_b64 s[12:13], 0x8000
	v_mov_b32_e32 v181, 0x110000
	s_nop 0
	s_nop 0
	s_branch .LBB0_1528

; DI void xcd_barrier(const XcdBarrier& b, int tid) {
;     asm volatile("s_waitcnt vmcnt(0)" ::: "memory");
;     __syncthreads();
;     if (tid == 0) {
;         unsigned* bar = b.bar;
;         __builtin_amdgcn_s_waitcnt(0);
;         unsigned nloc = b.st[0], nx = b.st[1];
;         if (nloc == 0u) { xcd_barrier_complete(bar, b.x, nloc, nx); b.st[0] = nloc; b.st[1] = nx; }
.LBB0_1547:
	s_nop 0
	s_nop 0
	s_nop 0
	s_nop 0
	s_nop 0
	s_nop 0
	s_nop 0
	s_nop 0
	s_nop 0
	s_nop 0
	s_nop 0
	s_nop 0
	s_nop 0
	s_nop 0
	v_mbcnt_lo_u32_b32 v0, -1, 0
	v_mbcnt_hi_u32_b32 v0, -1, v0
	s_nop 0
	v_add_u32_e32 v0, s74, v0
	s_waitcnt vmcnt(0)
	s_waitcnt vmcnt(63) expcnt(7) lgkmcnt(15)
	v_cmp_eq_u32_e32 vcc, 0, v0
	s_barrier
	s_and_saveexec_b64 s[0:1], vcc
	v_readlane_b32 s59, v254, 12
	s_cbranch_execz .LBB0_1599
	s_add_i32 s2, 0, 0x23ff0
	v_mov_b32_e32 v0, s2
	s_waitcnt vmcnt(0) expcnt(0) lgkmcnt(0)
	ds_read_b32 v2, v0
	s_add_i32 s2, 0, 0x23ff4
	v_mov_b32_e32 v0, s2
	ds_read_b32 v0, v0
	s_waitcnt lgkmcnt(1)
	v_cmp_ne_u32_e32 vcc, 0, v2
	s_cbranch_vccnz .LBB0_1563
	s_mov_b32 s2, 1
	v_mov_b32_e32 v16, 0
	s_branch .LBB0_1551
